# hand-written E_FFN1 epilogue arm (same ops and order as baseline, packed mul/add, no per-element address math)
# speedup vs baseline: 1.0728x; 1.0070x over previous
; #define PG8_STAGE(bufoff, gbase, voff) do { _Pragma("unroll") for (int _i = 0; _i < 2; ++_i) \
;         __builtin_amdgcn_global_load_lds((const unsigned*)((const char*)(gbase) + (voff)[_i]), (LAS unsigned*)(lds + (bufoff) + ldsw + _i * 8192), 16, 0, 0); } while (0)
; #define PG8_LDA(dst, b, h) do { _Pragma("unroll") for (int m = 0; m < 4; ++m) _Pragma("unroll") for (int k = 0; k < 2; ++k) dst[m][k] = *(const LAS bf16x8*)(lds + PG8_SA(b, h) + aoff + m * 2048 + k * 1024); } while (0)
; #define PG8_LDB(dst, b, h) do { _Pragma("unroll") for (int n = 0; n < 2; ++n) _Pragma("unroll") for (int k = 0; k < 2; ++k) dst[n][k] = *(const LAS bf16x8*)(lds + PG8_SB(b, h) + boff + n * 2048 + k * 1024); } while (0)
; #define PG8_MMA(ai, bj, At, Bt) do { __builtin_amdgcn_s_setprio(1); _Pragma("unroll") for (int m = 0; m < 4; ++m) _Pragma("unroll") for (int n = 0; n < 2; ++n) _Pragma("unroll") for (int k = 0; k < 2; ++k) \
;         acc[ai][bj][m][n] = __builtin_amdgcn_mfma_f32_16x16x32_bf16(Bt[n][k], At[m][k], acc[ai][bj][m][n], 0, 0, 0); __builtin_amdgcn_s_setprio(0); } while (0)
; #define PG8_WAIT_L(n) asm volatile("s_waitcnt lgkmcnt(" #n ")" ::: "memory")
; #define PG8_BAR __builtin_amdgcn_s_barrier()
; #define PG8_SCHED __builtin_amdgcn_sched_barrier(0)
; __device__ __forceinline__ void gemm_phase(LAS unsigned char* lds, CParams& p, const Job& jb) {
;     ...
;             PG8_LDB(B0, 0, 0); PG8_SCHED; PG8_LDA(At, 0, 0); PG8_STAGE(PG8_SA(1, 1), a1 + hstepA, voffA);
;             PG8_WAIT_L(8); PG8_BAR; PG8_WAIT_L(0); PG8_MMA(0, 0, At, B0); PG8_BAR; PG8_SCHED;
;             PG8_LDB(B1, 0, 1); PG8_STAGE(PG8_SB(0, 0), b2, voffB);
;             PG8_BAR; PG8_WAIT_L(0); PG8_MMA(0, 1, At, B1); PG8_BAR;
;             PG8_LDA(At, 0, 1); PG8_STAGE(PG8_SA(0, 0), a2, voffA);
;             PG8_BAR; PG8_WAIT_L(0); PG8_MMA(1, 0, At, B0); PG8_BAR; PG8_SCHED;
.LBB0_631:
	s_add_i32 s1, s1, 2
	s_add_u32 s12, s24, s10
	s_addc_u32 s13, s25, s11
	s_add_u32 s12, s12, 0x100
	s_addc_u32 s13, s13, 0
	s_add_u32 s14, s97, s10
	s_addc_u32 s15, s2, s11
	s_add_i32 s16, 0, 0x10000
	v_add_u32_e32 v144, s16, v213
	ds_read_b128 v[132:135], v144
	ds_read_b128 v[136:139], v144 offset:1024
	ds_read_b128 v[140:143], v144 offset:2048
	ds_read_b128 v[144:147], v144 offset:3072
	s_cmp_eq_u32 s85, s10
	s_cselect_b32 s13, s5, s13
	s_cselect_b32 s12, s4, s12
	s_cselect_b32 s15, s87, s15
	s_cselect_b32 s14, s86, s14
	v_lshl_add_u64 v[216:217], v[128:129], 0, s[10:11]
	s_add_i32 m0, s65, 0xc000
	ds_read_b128 v[148:151], v214
	ds_read_b128 v[152:155], v214 offset:1024
	ds_read_b128 v[156:159], v214 offset:2048
	ds_read_b128 v[172:175], v214 offset:3072
	ds_read_b128 v[176:179], v214 offset:4096
	ds_read_b128 v[180:183], v214 offset:5120
	ds_read_b128 v[184:187], v214 offset:6144
	ds_read_b128 v[188:191], v214 offset:7168
	global_load_lds_dwordx4 v[216:217], off
	v_lshl_add_u64 v[216:217], v[130:131], 0, s[10:11]
	s_add_i32 m0, s65, 0xe000
	s_nop 0
	global_load_lds_dwordx4 v[216:217], off
	s_waitcnt lgkmcnt(8)
	s_barrier
	s_waitcnt lgkmcnt(0)
	s_setprio 1
	s_waitcnt lgkmcnt(0)
	v_mfma_f32_16x16x32_bf16 v[124:127], v[132:135], v[148:151], v[124:127]
	v_mfma_f32_16x16x32_bf16 v[120:123], v[140:143], v[148:151], v[120:123]
	v_mfma_f32_16x16x32_bf16 v[116:119], v[132:135], v[156:159], v[116:119]
	v_mfma_f32_16x16x32_bf16 v[112:115], v[140:143], v[156:159], v[112:115]
	v_mfma_f32_16x16x32_bf16 v[108:111], v[132:135], v[176:179], v[108:111]
	v_mfma_f32_16x16x32_bf16 v[104:107], v[140:143], v[176:179], v[104:107]
	v_mfma_f32_16x16x32_bf16 v[100:103], v[132:135], v[184:187], v[100:103]
	v_mfma_f32_16x16x32_bf16 v[96:99], v[140:143], v[184:187], v[96:99]
	v_mfma_f32_16x16x32_bf16 v[124:127], v[136:139], v[152:155], v[124:127]
	v_mfma_f32_16x16x32_bf16 v[120:123], v[144:147], v[152:155], v[120:123]
	v_mfma_f32_16x16x32_bf16 v[116:119], v[136:139], v[172:175], v[116:119]
	v_mfma_f32_16x16x32_bf16 v[112:115], v[144:147], v[172:175], v[112:115]
	v_mfma_f32_16x16x32_bf16 v[108:111], v[136:139], v[180:183], v[108:111]
	v_mfma_f32_16x16x32_bf16 v[104:107], v[144:147], v[180:183], v[104:107]
	v_mfma_f32_16x16x32_bf16 v[100:103], v[136:139], v[188:191], v[100:103]
	v_mfma_f32_16x16x32_bf16 v[96:99], v[144:147], v[188:191], v[96:99]
	s_setprio 0
	s_barrier
	s_add_i32 s17, 0, 0x14000
	s_add_i32 s16, s16, s64
	v_add_u32_e32 v215, s17, v213
	v_lshl_add_u64 v[232:233], s[14:15], 0, v[160:161]
	s_mov_b32 m0, s16
	ds_read_b128 v[216:219], v215
	ds_read_b128 v[220:223], v215 offset:1024
	ds_read_b128 v[224:227], v215 offset:2048
	ds_read_b128 v[228:231], v215 offset:3072
	global_load_lds_dwordx4 v[232:233], off
	v_lshl_add_u64 v[234:235], s[14:15], 0, v[166:167]
	s_add_i32 m0, s16, 0x2000
	s_nop 0
	global_load_lds_dwordx4 v[234:235], off
	s_barrier
	s_waitcnt lgkmcnt(0)
	s_setprio 1
	s_waitcnt lgkmcnt(0)
	v_mfma_f32_16x16x32_bf16 v[92:95], v[216:219], v[148:151], v[92:95]
	v_mfma_f32_16x16x32_bf16 v[88:91], v[224:227], v[148:151], v[88:91]
	v_mfma_f32_16x16x32_bf16 v[84:87], v[216:219], v[156:159], v[84:87]
	v_mfma_f32_16x16x32_bf16 v[80:83], v[224:227], v[156:159], v[80:83]
	v_mfma_f32_16x16x32_bf16 v[76:79], v[216:219], v[176:179], v[76:79]
	v_mfma_f32_16x16x32_bf16 v[72:75], v[224:227], v[176:179], v[72:75]
	v_mfma_f32_16x16x32_bf16 v[68:71], v[216:219], v[184:187], v[68:71]
	v_mfma_f32_16x16x32_bf16 v[64:67], v[224:227], v[184:187], v[64:67]
	v_mfma_f32_16x16x32_bf16 v[92:95], v[220:223], v[152:155], v[92:95]
	v_mfma_f32_16x16x32_bf16 v[88:91], v[228:231], v[152:155], v[88:91]
	v_mfma_f32_16x16x32_bf16 v[84:87], v[220:223], v[172:175], v[84:87]
	v_mfma_f32_16x16x32_bf16 v[80:83], v[228:231], v[172:175], v[80:83]
	v_mfma_f32_16x16x32_bf16 v[76:79], v[220:223], v[180:183], v[76:79]
	v_mfma_f32_16x16x32_bf16 v[72:75], v[228:231], v[180:183], v[72:75]
	v_mfma_f32_16x16x32_bf16 v[68:71], v[220:223], v[188:191], v[68:71]
	v_mfma_f32_16x16x32_bf16 v[64:67], v[228:231], v[188:191], v[64:67]
	s_setprio 0
	s_mov_b32 m0, s65
	v_lshl_add_u64 v[236:237], s[12:13], 0, v[162:163]
	s_barrier
	ds_read_b128 v[148:151], v214 offset:16384
	ds_read_b128 v[152:155], v214 offset:17408
	ds_read_b128 v[156:159], v214 offset:18432
	ds_read_b128 v[172:175], v214 offset:19456
	ds_read_b128 v[176:179], v214 offset:20480
	ds_read_b128 v[180:183], v214 offset:21504
	ds_read_b128 v[184:187], v214 offset:22528
	ds_read_b128 v[188:191], v214 offset:23552
	global_load_lds_dwordx4 v[236:237], off
	v_lshl_add_u64 v[238:239], s[12:13], 0, v[164:165]
	s_mov_b32 m0, s66
	s_nop 0
	global_load_lds_dwordx4 v[238:239], off
	s_barrier
	s_waitcnt lgkmcnt(0)
	s_setprio 1
	s_waitcnt lgkmcnt(0)
	v_mfma_f32_16x16x32_bf16 v[60:63], v[132:135], v[148:151], v[60:63]
	v_mfma_f32_16x16x32_bf16 v[56:59], v[140:143], v[148:151], v[56:59]
	v_mfma_f32_16x16x32_bf16 v[52:55], v[132:135], v[156:159], v[52:55]
	v_mfma_f32_16x16x32_bf16 v[48:51], v[140:143], v[156:159], v[48:51]
	v_mfma_f32_16x16x32_bf16 v[44:47], v[132:135], v[176:179], v[44:47]
	v_mfma_f32_16x16x32_bf16 v[40:43], v[140:143], v[176:179], v[40:43]
	v_mfma_f32_16x16x32_bf16 v[36:39], v[132:135], v[184:187], v[36:39]
	v_mfma_f32_16x16x32_bf16 v[32:35], v[140:143], v[184:187], v[32:35]
	v_mfma_f32_16x16x32_bf16 v[60:63], v[136:139], v[152:155], v[60:63]
	v_mfma_f32_16x16x32_bf16 v[56:59], v[144:147], v[152:155], v[56:59]
	v_mfma_f32_16x16x32_bf16 v[52:55], v[136:139], v[172:175], v[52:55]
	v_mfma_f32_16x16x32_bf16 v[48:51], v[144:147], v[172:175], v[48:51]
	v_mfma_f32_16x16x32_bf16 v[44:47], v[136:139], v[180:183], v[44:47]
	v_mfma_f32_16x16x32_bf16 v[40:43], v[144:147], v[180:183], v[40:43]
	v_mfma_f32_16x16x32_bf16 v[36:39], v[136:139], v[188:191], v[36:39]
	v_mfma_f32_16x16x32_bf16 v[32:35], v[144:147], v[188:191], v[32:35]
	s_setprio 0
	s_barrier
; #define PG8_STAGE(bufoff, gbase, voff) do { _Pragma("unroll") for (int _i = 0; _i < 2; ++_i) \
;         __builtin_amdgcn_global_load_lds((const unsigned*)((const char*)(gbase) + (voff)[_i]), (LAS unsigned*)(lds + (bufoff) + ldsw + _i * 8192), 16, 0, 0); } while (0)
; #define PG8_LDA(dst, b, h) do { _Pragma("unroll") for (int m = 0; m < 4; ++m) _Pragma("unroll") for (int k = 0; k < 2; ++k) dst[m][k] = *(const LAS bf16x8*)(lds + PG8_SA(b, h) + aoff + m * 2048 + k * 1024); } while (0)
; #define PG8_LDB(dst, b, h) do { _Pragma("unroll") for (int n = 0; n < 2; ++n) _Pragma("unroll") for (int k = 0; k < 2; ++k) dst[n][k] = *(const LAS bf16x8*)(lds + PG8_SB(b, h) + boff + n * 2048 + k * 1024); } while (0)
; #define PG8_MMA(ai, bj, At, Bt) do { __builtin_amdgcn_s_setprio(1); _Pragma("unroll") for (int m = 0; m < 4; ++m) _Pragma("unroll") for (int n = 0; n < 2; ++n) _Pragma("unroll") for (int k = 0; k < 2; ++k) \
;         acc[ai][bj][m][n] = __builtin_amdgcn_mfma_f32_16x16x32_bf16(Bt[n][k], At[m][k], acc[ai][bj][m][n], 0, 0, 0); __builtin_amdgcn_s_setprio(0); } while (0)
; #define PG8_WAIT_V(n) asm volatile("s_waitcnt vmcnt(" #n ")" ::: "memory")
; #define PG8_WAIT_L(n) asm volatile("s_waitcnt lgkmcnt(" #n ")" ::: "memory")
; #define PG8_BAR __builtin_amdgcn_s_barrier()
; #define PG8_SCHED __builtin_amdgcn_sched_barrier(0)
; __device__ __forceinline__ void gemm_phase(LAS unsigned char* lds, CParams& p, const Job& jb) {
;     ...
;             PG8_STAGE(PG8_SB(0, 1), b2 + hstepB, voffB);
;             PG8_WAIT_V(6); PG8_BAR; PG8_MMA(1, 1, At, B1); PG8_BAR;
;             PG8_LDB(B0, 1, 0); PG8_SCHED; PG8_LDA(At, 1, 0); PG8_STAGE(PG8_SA(0, 1), a2 + hstepA, voffA);
;             PG8_WAIT_L(8); PG8_BAR; PG8_WAIT_L(0); PG8_MMA(0, 0, At, B0); PG8_BAR; PG8_SCHED;
;             PG8_LDB(B1, 1, 1); PG8_STAGE(PG8_SB(1, 0), b3, voffB);
;             PG8_BAR; PG8_WAIT_L(0); PG8_MMA(0, 1, At, B1); PG8_BAR;
;             PG8_LDA(At, 1, 1); PG8_STAGE(PG8_SA(1, 0), a3, voffA);
;             PG8_BAR; PG8_WAIT_L(0); PG8_MMA(1, 0, At, B0); PG8_BAR; PG8_SCHED;
	s_add_u32 s14, s14, s76
	s_addc_u32 s15, s15, s77
	s_add_i32 s16, s17, s64
	v_lshl_add_u64 v[240:241], s[14:15], 0, v[160:161]
	s_mov_b32 m0, s16
	v_lshl_add_u64 v[242:243], s[14:15], 0, v[166:167]
	global_load_lds_dwordx4 v[240:241], off
	s_add_i32 m0, s16, 0x2000
	s_nop 0
	global_load_lds_dwordx4 v[242:243], off
	s_waitcnt vmcnt(6)
	s_barrier
	s_setprio 1
	v_mfma_f32_16x16x32_bf16 v[28:31], v[216:219], v[148:151], v[28:31]
	v_mfma_f32_16x16x32_bf16 v[24:27], v[224:227], v[148:151], v[24:27]
	v_mfma_f32_16x16x32_bf16 v[20:23], v[216:219], v[156:159], v[20:23]
	v_mfma_f32_16x16x32_bf16 v[16:19], v[224:227], v[156:159], v[16:19]
	v_mfma_f32_16x16x32_bf16 v[12:15], v[216:219], v[176:179], v[12:15]
	v_mfma_f32_16x16x32_bf16 v[8:11], v[224:227], v[176:179], v[8:11]
	v_mfma_f32_16x16x32_bf16 v[4:7], v[216:219], v[184:187], v[4:7]
	v_mfma_f32_16x16x32_bf16 v[0:3], v[224:227], v[184:187], v[0:3]
	v_mfma_f32_16x16x32_bf16 v[28:31], v[220:223], v[152:155], v[28:31]
	v_mfma_f32_16x16x32_bf16 v[24:27], v[228:231], v[152:155], v[24:27]
	v_mfma_f32_16x16x32_bf16 v[20:23], v[220:223], v[172:175], v[20:23]
	v_mfma_f32_16x16x32_bf16 v[16:19], v[228:231], v[172:175], v[16:19]
	v_mfma_f32_16x16x32_bf16 v[12:15], v[220:223], v[180:183], v[12:15]
	v_mfma_f32_16x16x32_bf16 v[8:11], v[228:231], v[180:183], v[8:11]
	v_mfma_f32_16x16x32_bf16 v[4:7], v[220:223], v[188:191], v[4:7]
	v_mfma_f32_16x16x32_bf16 v[0:3], v[228:231], v[188:191], v[0:3]
	s_setprio 0
	s_add_i32 s14, 0, 0x18000
	v_add_u32_e32 v144, s14, v213
	s_barrier
	ds_read_b128 v[132:135], v144
	ds_read_b128 v[136:139], v144 offset:1024
	ds_read_b128 v[140:143], v144 offset:2048
	ds_read_b128 v[144:147], v144 offset:3072
	s_add_u32 s12, s12, s74
	s_addc_u32 s13, s13, s75
	s_mov_b32 m0, s67
	v_lshl_add_u64 v[216:217], s[12:13], 0, v[162:163]
	ds_read_b128 v[148:151], v214 offset:32768
	ds_read_b128 v[152:155], v214 offset:33792
	ds_read_b128 v[156:159], v214 offset:34816
	ds_read_b128 v[172:175], v214 offset:35840
	ds_read_b128 v[176:179], v214 offset:36864
	ds_read_b128 v[180:183], v214 offset:37888
	ds_read_b128 v[184:187], v214 offset:38912
	ds_read_b128 v[188:191], v214 offset:39936
	global_load_lds_dwordx4 v[216:217], off
	v_lshl_add_u64 v[216:217], s[12:13], 0, v[164:165]
	s_mov_b32 m0, s94
	s_nop 0
	global_load_lds_dwordx4 v[216:217], off
	s_waitcnt lgkmcnt(8)
	s_barrier
	s_waitcnt lgkmcnt(0)
	s_setprio 1
	s_waitcnt lgkmcnt(0)
	v_mfma_f32_16x16x32_bf16 v[124:127], v[132:135], v[148:151], v[124:127]
	v_mfma_f32_16x16x32_bf16 v[120:123], v[140:143], v[148:151], v[120:123]
	v_mfma_f32_16x16x32_bf16 v[116:119], v[132:135], v[156:159], v[116:119]
	v_mfma_f32_16x16x32_bf16 v[112:115], v[140:143], v[156:159], v[112:115]
	v_mfma_f32_16x16x32_bf16 v[108:111], v[132:135], v[176:179], v[108:111]
	v_mfma_f32_16x16x32_bf16 v[104:107], v[140:143], v[176:179], v[104:107]
	v_mfma_f32_16x16x32_bf16 v[100:103], v[132:135], v[184:187], v[100:103]
	v_mfma_f32_16x16x32_bf16 v[96:99], v[140:143], v[184:187], v[96:99]
	v_mfma_f32_16x16x32_bf16 v[124:127], v[136:139], v[152:155], v[124:127]
	v_mfma_f32_16x16x32_bf16 v[120:123], v[144:147], v[152:155], v[120:123]
	v_mfma_f32_16x16x32_bf16 v[116:119], v[136:139], v[172:175], v[116:119]
	v_mfma_f32_16x16x32_bf16 v[112:115], v[144:147], v[172:175], v[112:115]
	v_mfma_f32_16x16x32_bf16 v[108:111], v[136:139], v[180:183], v[108:111]
	v_mfma_f32_16x16x32_bf16 v[104:107], v[144:147], v[180:183], v[104:107]
	v_mfma_f32_16x16x32_bf16 v[100:103], v[136:139], v[188:191], v[100:103]
	v_mfma_f32_16x16x32_bf16 v[96:99], v[144:147], v[188:191], v[96:99]
	s_setprio 0
	s_barrier
	s_add_i32 s12, 0, 0x1c000
	s_add_i32 s13, s14, s64
	v_add_u32_e32 v215, s12, v213
	v_lshl_add_u64 v[232:233], v[232:233], 0, s[90:91]
	s_mov_b32 m0, s13
	ds_read_b128 v[216:219], v215
	ds_read_b128 v[220:223], v215 offset:1024
	ds_read_b128 v[224:227], v215 offset:2048
	ds_read_b128 v[228:231], v215 offset:3072
	global_load_lds_dwordx4 v[232:233], off
	v_lshl_add_u64 v[232:233], v[234:235], 0, s[90:91]
	s_add_i32 m0, s13, 0x2000
	s_nop 0
	global_load_lds_dwordx4 v[232:233], off
	s_barrier
	s_waitcnt lgkmcnt(0)
	s_setprio 1
	s_waitcnt lgkmcnt(0)
	v_mfma_f32_16x16x32_bf16 v[92:95], v[216:219], v[148:151], v[92:95]
	v_mfma_f32_16x16x32_bf16 v[88:91], v[224:227], v[148:151], v[88:91]
	v_mfma_f32_16x16x32_bf16 v[84:87], v[216:219], v[156:159], v[84:87]
	v_mfma_f32_16x16x32_bf16 v[80:83], v[224:227], v[156:159], v[80:83]
	v_mfma_f32_16x16x32_bf16 v[76:79], v[216:219], v[176:179], v[76:79]
	v_mfma_f32_16x16x32_bf16 v[72:75], v[224:227], v[176:179], v[72:75]
	v_mfma_f32_16x16x32_bf16 v[68:71], v[216:219], v[184:187], v[68:71]
	v_mfma_f32_16x16x32_bf16 v[64:67], v[224:227], v[184:187], v[64:67]
	v_mfma_f32_16x16x32_bf16 v[92:95], v[220:223], v[152:155], v[92:95]
	v_mfma_f32_16x16x32_bf16 v[88:91], v[228:231], v[152:155], v[88:91]
	v_mfma_f32_16x16x32_bf16 v[84:87], v[220:223], v[172:175], v[84:87]
	v_mfma_f32_16x16x32_bf16 v[80:83], v[228:231], v[172:175], v[80:83]
	v_mfma_f32_16x16x32_bf16 v[76:79], v[220:223], v[180:183], v[76:79]
	v_mfma_f32_16x16x32_bf16 v[72:75], v[228:231], v[180:183], v[72:75]
	v_mfma_f32_16x16x32_bf16 v[68:71], v[220:223], v[188:191], v[68:71]
	v_mfma_f32_16x16x32_bf16 v[64:67], v[228:231], v[188:191], v[64:67]
	s_setprio 0
	s_mov_b32 m0, s33
	v_lshl_add_u64 v[232:233], v[236:237], 0, s[90:91]
	s_barrier
	ds_read_b128 v[148:151], v214 offset:49152
	ds_read_b128 v[152:155], v214 offset:50176
	ds_read_b128 v[156:159], v214 offset:51200
	ds_read_b128 v[172:175], v214 offset:52224
	ds_read_b128 v[176:179], v214 offset:53248
	ds_read_b128 v[180:183], v214 offset:54272
	ds_read_b128 v[184:187], v214 offset:55296
	ds_read_b128 v[188:191], v214 offset:56320
	global_load_lds_dwordx4 v[232:233], off
	v_lshl_add_u64 v[232:233], v[238:239], 0, s[90:91]
	s_mov_b32 m0, s60
	s_nop 0
	global_load_lds_dwordx4 v[232:233], off
	s_barrier
; #define FOR_ROWS _Pragma("unroll") for (int ai = 0; ai < 2; ++ai) _Pragma("unroll") for (int m = 0; m < 4; ++m)
; #define PG8_STAGE(bufoff, gbase, voff) do { _Pragma("unroll") for (int _i = 0; _i < 2; ++_i) \
;         __builtin_amdgcn_global_load_lds((const unsigned*)((const char*)(gbase) + (voff)[_i]), (LAS unsigned*)(lds + (bufoff) + ldsw + _i * 8192), 16, 0, 0); } while (0)
; #define PG8_MMA(ai, bj, At, Bt) do { __builtin_amdgcn_s_setprio(1); _Pragma("unroll") for (int m = 0; m < 4; ++m) _Pragma("unroll") for (int n = 0; n < 2; ++n) _Pragma("unroll") for (int k = 0; k < 2; ++k) \
;         acc[ai][bj][m][n] = __builtin_amdgcn_mfma_f32_16x16x32_bf16(Bt[n][k], At[m][k], acc[ai][bj][m][n], 0, 0, 0); __builtin_amdgcn_s_setprio(0); } while (0)
; #define PG8_WAIT_V(n) asm volatile("s_waitcnt vmcnt(" #n ")" ::: "memory")
; #define PG8_WAIT_L(n) asm volatile("s_waitcnt lgkmcnt(" #n ")" ::: "memory")
; #define PG8_BAR __builtin_amdgcn_s_barrier()
; #define PG8_SCHED __builtin_amdgcn_sched_barrier(0)
; __device__ __forceinline__ void epilogue(const int kind, CParams& p, const f32x4 (&acc)[2][2][4][2], const Unit& u, const int wr, const int wc, const int fr_in, const int fq_in) {
;     ...
;     case E_DOWN_HALF: {
;         FOR_ROWS { ROWDEF
; #pragma unroll
;             for (int bj = 0; bj < 2; ++bj) { float* hp = p.out + row * 1024 + u.pn * 256 + bj * 128 + cw;
; #pragma unroll
;                 for (int j = 0; j < 4; ++j) { unsafeAtomicAdd(hp + j, acc[ai][bj][m][0][j]); unsafeAtomicAdd(hp + 4 + j, acc[ai][bj][m][1][j]); } } }
;     } break;
; __device__ __forceinline__ void gemm_phase(LAS unsigned char* lds, CParams& p, const Job& jb) {
;     ...
;             PG8_BAR; PG8_WAIT_L(0); PG8_MMA(1, 0, At, B0); PG8_BAR; PG8_SCHED;
;             PG8_STAGE(PG8_SB(1, 1), b3 + hstepB, voffB);
;             PG8_WAIT_V(6); PG8_BAR; PG8_MMA(1, 1, At, B1); PG8_BAR;
;         }
;         epilogue(cur.kind, p, acc, cur, wr, wc, fr, fq);
	s_waitcnt lgkmcnt(0)
	s_setprio 1
	s_waitcnt lgkmcnt(0)
	v_mfma_f32_16x16x32_bf16 v[60:63], v[132:135], v[148:151], v[60:63]
	v_mfma_f32_16x16x32_bf16 v[56:59], v[140:143], v[148:151], v[56:59]
	v_mfma_f32_16x16x32_bf16 v[52:55], v[132:135], v[156:159], v[52:55]
	v_mfma_f32_16x16x32_bf16 v[48:51], v[140:143], v[156:159], v[48:51]
	v_mfma_f32_16x16x32_bf16 v[44:47], v[132:135], v[176:179], v[44:47]
	v_mfma_f32_16x16x32_bf16 v[40:43], v[140:143], v[176:179], v[40:43]
	v_mfma_f32_16x16x32_bf16 v[36:39], v[132:135], v[184:187], v[36:39]
	v_mfma_f32_16x16x32_bf16 v[32:35], v[140:143], v[184:187], v[32:35]
	v_mfma_f32_16x16x32_bf16 v[60:63], v[136:139], v[152:155], v[60:63]
	v_mfma_f32_16x16x32_bf16 v[56:59], v[144:147], v[152:155], v[56:59]
	v_mfma_f32_16x16x32_bf16 v[52:55], v[136:139], v[172:175], v[52:55]
	v_mfma_f32_16x16x32_bf16 v[48:51], v[144:147], v[172:175], v[48:51]
	v_mfma_f32_16x16x32_bf16 v[44:47], v[136:139], v[180:183], v[44:47]
	v_mfma_f32_16x16x32_bf16 v[40:43], v[144:147], v[180:183], v[40:43]
	v_mfma_f32_16x16x32_bf16 v[36:39], v[136:139], v[188:191], v[36:39]
	v_mfma_f32_16x16x32_bf16 v[32:35], v[144:147], v[188:191], v[32:35]
	s_setprio 0
	s_barrier
	s_add_i32 s12, s12, s64
	v_lshl_add_u64 v[132:133], v[240:241], 0, s[90:91]
	s_mov_b32 m0, s12
	s_nop 0
	global_load_lds_dwordx4 v[132:133], off
	v_lshl_add_u64 v[132:133], v[242:243], 0, s[90:91]
	s_add_i32 m0, s12, 0x2000
	s_nop 0
	global_load_lds_dwordx4 v[132:133], off
	s_waitcnt vmcnt(6)
	s_barrier
	s_setprio 1
	v_mfma_f32_16x16x32_bf16 v[28:31], v[216:219], v[148:151], v[28:31]
	v_mfma_f32_16x16x32_bf16 v[24:27], v[224:227], v[148:151], v[24:27]
	v_mfma_f32_16x16x32_bf16 v[20:23], v[216:219], v[156:159], v[20:23]
	v_mfma_f32_16x16x32_bf16 v[16:19], v[224:227], v[156:159], v[16:19]
	v_mfma_f32_16x16x32_bf16 v[12:15], v[216:219], v[176:179], v[12:15]
	v_mfma_f32_16x16x32_bf16 v[8:11], v[224:227], v[176:179], v[8:11]
	v_mfma_f32_16x16x32_bf16 v[4:7], v[216:219], v[184:187], v[4:7]
	v_mfma_f32_16x16x32_bf16 v[0:3], v[224:227], v[184:187], v[0:3]
	v_mfma_f32_16x16x32_bf16 v[28:31], v[220:223], v[152:155], v[28:31]
	v_mfma_f32_16x16x32_bf16 v[24:27], v[228:231], v[152:155], v[24:27]
	v_mfma_f32_16x16x32_bf16 v[20:23], v[220:223], v[172:175], v[20:23]
	v_mfma_f32_16x16x32_bf16 v[16:19], v[228:231], v[172:175], v[16:19]
	v_mfma_f32_16x16x32_bf16 v[12:15], v[220:223], v[180:183], v[12:15]
	v_mfma_f32_16x16x32_bf16 v[8:11], v[228:231], v[180:183], v[8:11]
	v_mfma_f32_16x16x32_bf16 v[4:7], v[220:223], v[188:191], v[4:7]
	v_mfma_f32_16x16x32_bf16 v[0:3], v[228:231], v[188:191], v[0:3]
	s_setprio 0
	s_add_u32 s10, s10, 0x100
	s_addc_u32 s11, s11, 0
	s_cmp_ge_u32 s1, s84
	s_barrier
	s_cbranch_scc0 .LBB0_631
	v_mov_b32_e32 v215, v211
	v_mov_b32_e32 v216, v212
	s_cmp_eq_u32 s3, 13
	s_cbranch_scc1 .Lmy_down
	s_cmp_eq_u32 s3, 12
	s_cbranch_scc1 .Lmy_ffn1
	s_cmp_lt_i32 s3, 7
	v_lshl_add_u32 v172, v216, 3, s31
	s_mov_b64 s[10:11], -1
	s_cbranch_scc1 .LBB0_849
	s_cmp_lt_i32 s3, 11
	s_cbranch_scc1 .LBB0_639
	s_cmp_gt_i32 s3, 12
	s_cbranch_scc0 .LBB0_640
	s_cmp_gt_i32 s3, 13
	s_mov_b64 s[26:27], -1
	s_cbranch_scc0 .LBB0_641
	s_cmp_eq_u32 s3, 14
	s_cbranch_scc0 .LBB0_638
	v_add_u32_e32 v128, s0, v215
	s_ashr_i32 s79, s78, 31
	v_ashrrev_i32_e32 v129, 31, v128
	v_lshl_add_u64 v[130:131], v[128:129], 0, s[78:79]
	s_lshl_b32 s10, s92, 8
	v_lshlrev_b64 v[130:131], 12, v[130:131]
	s_ashr_i32 s11, s10, 31
	v_ashrrev_i32_e32 v173, 31, v172
	v_lshl_add_u64 v[130:131], s[82:83], 0, v[130:131]
	s_lshl_b64 s[10:11], s[10:11], 2
	v_lshl_add_u64 v[130:131], v[130:131], 0, s[10:11]
	v_lshlrev_b64 v[132:133], 2, v[172:173]
	v_lshl_add_u64 v[130:131], v[130:131], 0, v[132:133]
	global_atomic_add_f32 v[130:131], v124, off
	global_atomic_add_f32 v[130:131], v120, off offset:16
	global_atomic_add_f32 v[130:131], v125, off offset:4
	global_atomic_add_f32 v[130:131], v121, off offset:20
	global_atomic_add_f32 v[130:131], v126, off offset:8
	global_atomic_add_f32 v[130:131], v122, off offset:24
	global_atomic_add_f32 v[130:131], v127, off offset:12
	global_atomic_add_f32 v[130:131], v123, off offset:28
	global_atomic_add_f32 v[130:131], v92, off offset:512
	global_atomic_add_f32 v[130:131], v88, off offset:528
	global_atomic_add_f32 v[130:131], v93, off offset:516
	global_atomic_add_f32 v[130:131], v89, off offset:532
	global_atomic_add_f32 v[130:131], v94, off offset:520
	global_atomic_add_f32 v[130:131], v90, off offset:536
	global_atomic_add_f32 v[130:131], v95, off offset:524
	global_atomic_add_f32 v[130:131], v91, off offset:540
	v_add_u32_e32 v130, 16, v128
	v_ashrrev_i32_e32 v131, 31, v130
	v_lshl_add_u64 v[130:131], v[130:131], 0, s[78:79]
	v_lshlrev_b64 v[130:131], 12, v[130:131]
	v_lshl_add_u64 v[130:131], s[82:83], 0, v[130:131]
	v_lshl_add_u64 v[130:131], v[130:131], 0, s[10:11]
	v_lshl_add_u64 v[130:131], v[130:131], 0, v[132:133]
	global_atomic_add_f32 v[130:131], v116, off
	global_atomic_add_f32 v[130:131], v112, off offset:16
	global_atomic_add_f32 v[130:131], v117, off offset:4
	global_atomic_add_f32 v[130:131], v113, off offset:20
	global_atomic_add_f32 v[130:131], v118, off offset:8
	global_atomic_add_f32 v[130:131], v114, off offset:24
	global_atomic_add_f32 v[130:131], v119, off offset:12
	global_atomic_add_f32 v[130:131], v115, off offset:28
	global_atomic_add_f32 v[130:131], v84, off offset:512
	global_atomic_add_f32 v[130:131], v80, off offset:528
	global_atomic_add_f32 v[130:131], v85, off offset:516
	global_atomic_add_f32 v[130:131], v81, off offset:532
	global_atomic_add_f32 v[130:131], v86, off offset:520
	global_atomic_add_f32 v[130:131], v82, off offset:536
; #define FOR_ROWS _Pragma("unroll") for (int ai = 0; ai < 2; ++ai) _Pragma("unroll") for (int m = 0; m < 4; ++m)
; __device__ __forceinline__ void epilogue(const int kind, CParams& p, const f32x4 (&acc)[2][2][4][2], const Unit& u, const int wr, const int wc, const int fr_in, const int fq_in) {
;     ...
;         FOR_ROWS { ROWDEF
; #pragma unroll
;             for (int bj = 0; bj < 2; ++bj) { float* hp = p.out + row * 1024 + u.pn * 256 + bj * 128 + cw;
; #pragma unroll
;                 for (int j = 0; j < 4; ++j) { unsafeAtomicAdd(hp + j, acc[ai][bj][m][0][j]); unsafeAtomicAdd(hp + 4 + j, acc[ai][bj][m][1][j]); } } }
	global_atomic_add_f32 v[130:131], v87, off offset:524
	global_atomic_add_f32 v[130:131], v83, off offset:540
	v_add_u32_e32 v130, 32, v128
	v_ashrrev_i32_e32 v131, 31, v130
	v_lshl_add_u64 v[130:131], v[130:131], 0, s[78:79]
	v_lshlrev_b64 v[130:131], 12, v[130:131]
	v_lshl_add_u64 v[130:131], s[82:83], 0, v[130:131]
	v_lshl_add_u64 v[130:131], v[130:131], 0, s[10:11]
	v_lshl_add_u64 v[130:131], v[130:131], 0, v[132:133]
	global_atomic_add_f32 v[130:131], v108, off
	global_atomic_add_f32 v[130:131], v104, off offset:16
	global_atomic_add_f32 v[130:131], v109, off offset:4
	global_atomic_add_f32 v[130:131], v105, off offset:20
	global_atomic_add_f32 v[130:131], v110, off offset:8
	global_atomic_add_f32 v[130:131], v106, off offset:24
	global_atomic_add_f32 v[130:131], v111, off offset:12
	global_atomic_add_f32 v[130:131], v107, off offset:28
	global_atomic_add_f32 v[130:131], v76, off offset:512
	global_atomic_add_f32 v[130:131], v72, off offset:528
	global_atomic_add_f32 v[130:131], v77, off offset:516
	global_atomic_add_f32 v[130:131], v73, off offset:532
	global_atomic_add_f32 v[130:131], v78, off offset:520
	global_atomic_add_f32 v[130:131], v74, off offset:536
	global_atomic_add_f32 v[130:131], v79, off offset:524
	global_atomic_add_f32 v[130:131], v75, off offset:540
	v_add_u32_e32 v130, 48, v128
	v_ashrrev_i32_e32 v131, 31, v130
	v_lshl_add_u64 v[130:131], v[130:131], 0, s[78:79]
	v_lshlrev_b64 v[130:131], 12, v[130:131]
	v_lshl_add_u64 v[130:131], s[82:83], 0, v[130:131]
	v_lshl_add_u64 v[130:131], v[130:131], 0, s[10:11]
	v_lshl_add_u64 v[130:131], v[130:131], 0, v[132:133]
	global_atomic_add_f32 v[130:131], v100, off
	global_atomic_add_f32 v[130:131], v96, off offset:16
	global_atomic_add_f32 v[130:131], v101, off offset:4
	global_atomic_add_f32 v[130:131], v97, off offset:20
	global_atomic_add_f32 v[130:131], v102, off offset:8
	global_atomic_add_f32 v[130:131], v98, off offset:24
	global_atomic_add_f32 v[130:131], v103, off offset:12
	global_atomic_add_f32 v[130:131], v99, off offset:28
	global_atomic_add_f32 v[130:131], v68, off offset:512
	global_atomic_add_f32 v[130:131], v64, off offset:528
	global_atomic_add_f32 v[130:131], v69, off offset:516
	global_atomic_add_f32 v[130:131], v65, off offset:532
	global_atomic_add_f32 v[130:131], v70, off offset:520
	global_atomic_add_f32 v[130:131], v66, off offset:536
	global_atomic_add_f32 v[130:131], v71, off offset:524
	global_atomic_add_f32 v[130:131], v67, off offset:540
	v_add_u32_e32 v130, 0x80, v128
	v_ashrrev_i32_e32 v131, 31, v130
	v_lshl_add_u64 v[130:131], v[130:131], 0, s[78:79]
	v_lshlrev_b64 v[130:131], 12, v[130:131]
	v_lshl_add_u64 v[130:131], s[82:83], 0, v[130:131]
	v_lshl_add_u64 v[130:131], v[130:131], 0, s[10:11]
	v_lshl_add_u64 v[130:131], v[130:131], 0, v[132:133]
	global_atomic_add_f32 v[130:131], v60, off
	global_atomic_add_f32 v[130:131], v56, off offset:16
	global_atomic_add_f32 v[130:131], v61, off offset:4
	global_atomic_add_f32 v[130:131], v57, off offset:20
	global_atomic_add_f32 v[130:131], v62, off offset:8
	global_atomic_add_f32 v[130:131], v58, off offset:24
	global_atomic_add_f32 v[130:131], v63, off offset:12
	global_atomic_add_f32 v[130:131], v59, off offset:28
	global_atomic_add_f32 v[130:131], v28, off offset:512
	global_atomic_add_f32 v[130:131], v24, off offset:528
	global_atomic_add_f32 v[130:131], v29, off offset:516
	global_atomic_add_f32 v[130:131], v25, off offset:532
	global_atomic_add_f32 v[130:131], v30, off offset:520
	global_atomic_add_f32 v[130:131], v26, off offset:536
	global_atomic_add_f32 v[130:131], v31, off offset:524
; #define FOR_ROWS _Pragma("unroll") for (int ai = 0; ai < 2; ++ai) _Pragma("unroll") for (int m = 0; m < 4; ++m)
; __device__ __forceinline__ void epilogue(const int kind, CParams& p, const f32x4 (&acc)[2][2][4][2], const Unit& u, const int wr, const int wc, const int fr_in, const int fq_in) {
;     ...
;         FOR_ROWS { ROWDEF
; #pragma unroll
;             for (int bj = 0; bj < 2; ++bj) { float* hp = p.out + row * 1024 + u.pn * 256 + bj * 128 + cw;
; #pragma unroll
;                 for (int j = 0; j < 4; ++j) { unsafeAtomicAdd(hp + j, acc[ai][bj][m][0][j]); unsafeAtomicAdd(hp + 4 + j, acc[ai][bj][m][1][j]); } } }
	global_atomic_add_f32 v[130:131], v27, off offset:540
	v_add_u32_e32 v130, 0x90, v128
	v_ashrrev_i32_e32 v131, 31, v130
	v_lshl_add_u64 v[130:131], v[130:131], 0, s[78:79]
	v_lshlrev_b64 v[130:131], 12, v[130:131]
	v_lshl_add_u64 v[130:131], s[82:83], 0, v[130:131]
	v_lshl_add_u64 v[130:131], v[130:131], 0, s[10:11]
	v_lshl_add_u64 v[130:131], v[130:131], 0, v[132:133]
	global_atomic_add_f32 v[130:131], v52, off
	global_atomic_add_f32 v[130:131], v48, off offset:16
	global_atomic_add_f32 v[130:131], v53, off offset:4
	global_atomic_add_f32 v[130:131], v49, off offset:20
	global_atomic_add_f32 v[130:131], v54, off offset:8
	global_atomic_add_f32 v[130:131], v50, off offset:24
	global_atomic_add_f32 v[130:131], v55, off offset:12
	global_atomic_add_f32 v[130:131], v51, off offset:28
	global_atomic_add_f32 v[130:131], v20, off offset:512
	global_atomic_add_f32 v[130:131], v16, off offset:528
	global_atomic_add_f32 v[130:131], v21, off offset:516
	global_atomic_add_f32 v[130:131], v17, off offset:532
	global_atomic_add_f32 v[130:131], v22, off offset:520
	global_atomic_add_f32 v[130:131], v18, off offset:536
	global_atomic_add_f32 v[130:131], v23, off offset:524
	global_atomic_add_f32 v[130:131], v19, off offset:540
	v_add_u32_e32 v130, 0xa0, v128
	v_ashrrev_i32_e32 v131, 31, v130
	v_add_u32_e32 v128, 0xb0, v128
	v_lshl_add_u64 v[130:131], v[130:131], 0, s[78:79]
	v_ashrrev_i32_e32 v129, 31, v128
	v_lshlrev_b64 v[130:131], 12, v[130:131]
	v_lshl_add_u64 v[128:129], v[128:129], 0, s[78:79]
	v_lshl_add_u64 v[130:131], s[82:83], 0, v[130:131]
	v_lshlrev_b64 v[128:129], 12, v[128:129]
	v_lshl_add_u64 v[130:131], v[130:131], 0, s[10:11]
	v_lshl_add_u64 v[128:129], s[82:83], 0, v[128:129]
	v_lshl_add_u64 v[130:131], v[130:131], 0, v[132:133]
	v_lshl_add_u64 v[128:129], v[128:129], 0, s[10:11]
	global_atomic_add_f32 v[130:131], v44, off
	global_atomic_add_f32 v[130:131], v40, off offset:16
	global_atomic_add_f32 v[130:131], v45, off offset:4
	global_atomic_add_f32 v[130:131], v41, off offset:20
	global_atomic_add_f32 v[130:131], v46, off offset:8
	global_atomic_add_f32 v[130:131], v42, off offset:24
	global_atomic_add_f32 v[130:131], v47, off offset:12
	global_atomic_add_f32 v[130:131], v43, off offset:28
	global_atomic_add_f32 v[130:131], v12, off offset:512
	global_atomic_add_f32 v[130:131], v8, off offset:528
	global_atomic_add_f32 v[130:131], v13, off offset:516
	global_atomic_add_f32 v[130:131], v9, off offset:532
	global_atomic_add_f32 v[130:131], v14, off offset:520
	global_atomic_add_f32 v[130:131], v10, off offset:536
	global_atomic_add_f32 v[130:131], v15, off offset:524
	global_atomic_add_f32 v[130:131], v11, off offset:540
	v_lshl_add_u64 v[128:129], v[128:129], 0, v[132:133]
	global_atomic_add_f32 v[128:129], v36, off
	global_atomic_add_f32 v[128:129], v32, off offset:16
	global_atomic_add_f32 v[128:129], v37, off offset:4
	global_atomic_add_f32 v[128:129], v33, off offset:20
	global_atomic_add_f32 v[128:129], v38, off offset:8
	global_atomic_add_f32 v[128:129], v34, off offset:24
	global_atomic_add_f32 v[128:129], v39, off offset:12
	global_atomic_add_f32 v[128:129], v35, off offset:28
	global_atomic_add_f32 v[128:129], v4, off offset:512
	global_atomic_add_f32 v[128:129], v0, off offset:528
	global_atomic_add_f32 v[128:129], v5, off offset:516
	global_atomic_add_f32 v[128:129], v1, off offset:532
	global_atomic_add_f32 v[128:129], v6, off offset:520
	global_atomic_add_f32 v[128:129], v2, off offset:536
	global_atomic_add_f32 v[128:129], v7, off offset:524
	global_atomic_add_f32 v[128:129], v3, off offset:540

; __device__ __forceinline__ u32x4 pack8(f32x4 a, f32x4 b) { u32x4 w; w.x = pk2(a[0], a[1]); w.y = pk2(a[2], a[3]); w.z = pk2(b[0], b[1]); w.w = pk2(b[2], b[3]); return w; }
; __device__ __forceinline__ f32x4 sigm4(f32x4 v) { return (f32x4){sigm(v[0]), sigm(v[1]), sigm(v[2]), sigm(v[3])}; }
; #define FOR_ROWS _Pragma("unroll") for (int ai = 0; ai < 2; ++ai) _Pragma("unroll") for (int m = 0; m < 4; ++m)
; __device__ __forceinline__ void epilogue(const int kind, CParams& p, const f32x4 (&acc)[2][2][4][2], const Unit& u, const int wr, const int wc, const int fr_in, const int fq_in) {
;     ...
;     case E_FFN1: {
;         float rsv[2][4];
;         FOR_ROWS { ROWDEF rsv[ai][m] = p.ss2[row]; }
;         FOR_ROWS { ROWDEF
;             const float rs = rsqrtf(rsv[ai][m] * (1.f / 1024.f) + 1e-6f);
;             const f32x4 g0 = acc[ai][0][m][0] * rs, g1 = acc[ai][0][m][1] * rs, u0 = acc[ai][1][m][0] * rs, u1 = acc[ai][1][m][1] * rs;
;             *(u32x4*)(p.hid + row * DFF + u.pn * 128 + cw) = pack8(g0 * sigm4(g0) * u0, g1 * sigm4(g1) * u1);
;         }
;     } break;
.Lmy_ffn1:
	v_readlane_b32 s12, v245, 55
	v_readlane_b32 s13, v245, 56
	v_lshl_add_u32 v220, v216, 3, s31
	v_add_u32_e32 v224, s0, v215
	v_add_u32_e32 v224, s78, v224
	s_load_dwordx2 s[14:15], s[12:13], 0x1f8
	s_load_dwordx2 s[16:17], s[12:13], 0x1b0
	v_lshlrev_b32_e32 v225, 2, v224
	s_movk_i32 s1, 0x1600
	v_mul_lo_u32 v217, v224, s1
	s_lshl_b32 s1, s92, 8
	v_lshl_add_u32 v220, v220, 1, s1
	v_add_u32_e32 v217, v217, v220
	v_mov_b32_e32 v226, 0xbfb8aa3b
	v_mov_b32_e32 v227, 0xbfb8aa3b
	s_waitcnt lgkmcnt(0)
	global_load_dword v180, v225, s[16:17] offset:0
	global_load_dword v181, v225, s[16:17] offset:64
	global_load_dword v182, v225, s[16:17] offset:128
	global_load_dword v183, v225, s[16:17] offset:192
	global_load_dword v184, v225, s[16:17] offset:512
	global_load_dword v185, v225, s[16:17] offset:576
	global_load_dword v186, v225, s[16:17] offset:640
	global_load_dword v187, v225, s[16:17] offset:704
	s_waitcnt vmcnt(7)
	v_fmamk_f32 v180, v180, 0x3a800000, v193
	v_rsq_f32_e32 v180, v180
	v_mov_b32_e32 v218, v217
	v_pk_mul_f32 v[124:125], v[124:125], v[180:181] op_sel_hi:[1,0]
	v_pk_mul_f32 v[126:127], v[126:127], v[180:181] op_sel_hi:[1,0]
	v_pk_mul_f32 v[120:121], v[120:121], v[180:181] op_sel_hi:[1,0]
	v_pk_mul_f32 v[122:123], v[122:123], v[180:181] op_sel_hi:[1,0]
	v_pk_mul_f32 v[128:129], v[124:125], v[226:227]
	v_pk_mul_f32 v[130:131], v[126:127], v[226:227]
	v_pk_mul_f32 v[132:133], v[120:121], v[226:227]
	v_pk_mul_f32 v[134:135], v[122:123], v[226:227]
	v_pk_mul_f32 v[92:93], v[92:93], v[180:181] op_sel_hi:[1,0]
	v_pk_mul_f32 v[94:95], v[94:95], v[180:181] op_sel_hi:[1,0]
	v_pk_mul_f32 v[88:89], v[88:89], v[180:181] op_sel_hi:[1,0]
	v_pk_mul_f32 v[90:91], v[90:91], v[180:181] op_sel_hi:[1,0]
	v_exp_f32_e32 v128, v128
	v_exp_f32_e32 v129, v129
	v_exp_f32_e32 v130, v130
	v_exp_f32_e32 v131, v131
	v_exp_f32_e32 v132, v132
	v_exp_f32_e32 v133, v133
	v_exp_f32_e32 v134, v134
	v_exp_f32_e32 v135, v135
	v_pk_add_f32 v[128:129], v[128:129], 1.0 op_sel_hi:[1,0]
	v_pk_add_f32 v[130:131], v[130:131], 1.0 op_sel_hi:[1,0]
	v_pk_add_f32 v[132:133], v[132:133], 1.0 op_sel_hi:[1,0]
	v_pk_add_f32 v[134:135], v[134:135], 1.0 op_sel_hi:[1,0]
	v_rcp_f32_e32 v128, v128
	v_rcp_f32_e32 v129, v129
	v_rcp_f32_e32 v130, v130
	v_rcp_f32_e32 v131, v131
	v_rcp_f32_e32 v132, v132
	v_rcp_f32_e32 v133, v133
	v_rcp_f32_e32 v134, v134
	v_rcp_f32_e32 v135, v135
	v_pk_mul_f32 v[124:125], v[124:125], v[128:129]
	v_pk_mul_f32 v[126:127], v[126:127], v[130:131]
	v_pk_mul_f32 v[120:121], v[120:121], v[132:133]
	v_pk_mul_f32 v[122:123], v[122:123], v[134:135]
	v_pk_mul_f32 v[124:125], v[124:125], v[92:93]
	v_pk_mul_f32 v[126:127], v[126:127], v[94:95]
	v_pk_mul_f32 v[120:121], v[120:121], v[88:89]
	v_pk_mul_f32 v[122:123], v[122:123], v[90:91]
	v_cvt_pk_bf16_f32 v136, v124, v125
	v_cvt_pk_bf16_f32 v137, v126, v127
	v_cvt_pk_bf16_f32 v138, v120, v121
	v_cvt_pk_bf16_f32 v139, v122, v123
	global_store_dwordx4 v218, v[136:139], s[14:15]
	s_waitcnt vmcnt(7)
	v_fmamk_f32 v181, v181, 0x3a800000, v193
	v_rsq_f32_e32 v181, v181
	v_add_u32_e32 v219, 0x16000, v217
	v_pk_mul_f32 v[116:117], v[116:117], v[180:181] op_sel:[0,1] op_sel_hi:[1,1]
	v_pk_mul_f32 v[118:119], v[118:119], v[180:181] op_sel:[0,1] op_sel_hi:[1,1]
	v_pk_mul_f32 v[112:113], v[112:113], v[180:181] op_sel:[0,1] op_sel_hi:[1,1]
	v_pk_mul_f32 v[114:115], v[114:115], v[180:181] op_sel:[0,1] op_sel_hi:[1,1]
	v_pk_mul_f32 v[144:145], v[116:117], v[226:227]
	v_pk_mul_f32 v[146:147], v[118:119], v[226:227]
	v_pk_mul_f32 v[148:149], v[112:113], v[226:227]
	v_pk_mul_f32 v[150:151], v[114:115], v[226:227]
	v_pk_mul_f32 v[84:85], v[84:85], v[180:181] op_sel:[0,1] op_sel_hi:[1,1]
	v_pk_mul_f32 v[86:87], v[86:87], v[180:181] op_sel:[0,1] op_sel_hi:[1,1]
	v_pk_mul_f32 v[80:81], v[80:81], v[180:181] op_sel:[0,1] op_sel_hi:[1,1]
	v_pk_mul_f32 v[82:83], v[82:83], v[180:181] op_sel:[0,1] op_sel_hi:[1,1]
	v_exp_f32_e32 v144, v144
	v_exp_f32_e32 v145, v145
	v_exp_f32_e32 v146, v146
	v_exp_f32_e32 v147, v147
	v_exp_f32_e32 v148, v148
	v_exp_f32_e32 v149, v149
	v_exp_f32_e32 v150, v150
	v_exp_f32_e32 v151, v151
	v_pk_add_f32 v[144:145], v[144:145], 1.0 op_sel_hi:[1,0]
	v_pk_add_f32 v[146:147], v[146:147], 1.0 op_sel_hi:[1,0]
	v_pk_add_f32 v[148:149], v[148:149], 1.0 op_sel_hi:[1,0]
	v_pk_add_f32 v[150:151], v[150:151], 1.0 op_sel_hi:[1,0]
	v_rcp_f32_e32 v144, v144
	v_rcp_f32_e32 v145, v145
	v_rcp_f32_e32 v146, v146
	v_rcp_f32_e32 v147, v147
	v_rcp_f32_e32 v148, v148
	v_rcp_f32_e32 v149, v149
	v_rcp_f32_e32 v150, v150
	v_rcp_f32_e32 v151, v151
	v_pk_mul_f32 v[116:117], v[116:117], v[144:145]
	v_pk_mul_f32 v[118:119], v[118:119], v[146:147]
	v_pk_mul_f32 v[112:113], v[112:113], v[148:149]
	v_pk_mul_f32 v[114:115], v[114:115], v[150:151]
	v_pk_mul_f32 v[116:117], v[116:117], v[84:85]
	v_pk_mul_f32 v[118:119], v[118:119], v[86:87]
	v_pk_mul_f32 v[112:113], v[112:113], v[80:81]
	v_pk_mul_f32 v[114:115], v[114:115], v[82:83]
	v_cvt_pk_bf16_f32 v152, v116, v117
	v_cvt_pk_bf16_f32 v153, v118, v119
	v_cvt_pk_bf16_f32 v154, v112, v113
	v_cvt_pk_bf16_f32 v155, v114, v115
	global_store_dwordx4 v219, v[152:155], s[14:15]
	s_waitcnt vmcnt(7)
; __device__ __forceinline__ u32x4 pack8(f32x4 a, f32x4 b) { u32x4 w; w.x = pk2(a[0], a[1]); w.y = pk2(a[2], a[3]); w.z = pk2(b[0], b[1]); w.w = pk2(b[2], b[3]); return w; }
; __device__ __forceinline__ f32x4 sigm4(f32x4 v) { return (f32x4){sigm(v[0]), sigm(v[1]), sigm(v[2]), sigm(v[3])}; }
; #define FOR_ROWS _Pragma("unroll") for (int ai = 0; ai < 2; ++ai) _Pragma("unroll") for (int m = 0; m < 4; ++m)
; __device__ __forceinline__ void epilogue(const int kind, CParams& p, const f32x4 (&acc)[2][2][4][2], const Unit& u, const int wr, const int wc, const int fr_in, const int fq_in) {
;     ...
;     case E_FFN1: {
;         float rsv[2][4];
;         FOR_ROWS { ROWDEF rsv[ai][m] = p.ss2[row]; }
;         FOR_ROWS { ROWDEF
;             const float rs = rsqrtf(rsv[ai][m] * (1.f / 1024.f) + 1e-6f);
;             const f32x4 g0 = acc[ai][0][m][0] * rs, g1 = acc[ai][0][m][1] * rs, u0 = acc[ai][1][m][0] * rs, u1 = acc[ai][1][m][1] * rs;
;             *(u32x4*)(p.hid + row * DFF + u.pn * 128 + cw) = pack8(g0 * sigm4(g0) * u0, g1 * sigm4(g1) * u1);
;         }
;     } break;
	v_fmamk_f32 v182, v182, 0x3a800000, v193
	v_rsq_f32_e32 v182, v182
	v_add_u32_e32 v218, 0x2c000, v217
	v_pk_mul_f32 v[108:109], v[108:109], v[182:183] op_sel_hi:[1,0]
	v_pk_mul_f32 v[110:111], v[110:111], v[182:183] op_sel_hi:[1,0]
	v_pk_mul_f32 v[104:105], v[104:105], v[182:183] op_sel_hi:[1,0]
	v_pk_mul_f32 v[106:107], v[106:107], v[182:183] op_sel_hi:[1,0]
	v_pk_mul_f32 v[128:129], v[108:109], v[226:227]
	v_pk_mul_f32 v[130:131], v[110:111], v[226:227]
	v_pk_mul_f32 v[132:133], v[104:105], v[226:227]
	v_pk_mul_f32 v[134:135], v[106:107], v[226:227]
	v_pk_mul_f32 v[76:77], v[76:77], v[182:183] op_sel_hi:[1,0]
	v_pk_mul_f32 v[78:79], v[78:79], v[182:183] op_sel_hi:[1,0]
	v_pk_mul_f32 v[72:73], v[72:73], v[182:183] op_sel_hi:[1,0]
	v_pk_mul_f32 v[74:75], v[74:75], v[182:183] op_sel_hi:[1,0]
	v_exp_f32_e32 v128, v128
	v_exp_f32_e32 v129, v129
	v_exp_f32_e32 v130, v130
	v_exp_f32_e32 v131, v131
	v_exp_f32_e32 v132, v132
	v_exp_f32_e32 v133, v133
	v_exp_f32_e32 v134, v134
	v_exp_f32_e32 v135, v135
	v_pk_add_f32 v[128:129], v[128:129], 1.0 op_sel_hi:[1,0]
	v_pk_add_f32 v[130:131], v[130:131], 1.0 op_sel_hi:[1,0]
	v_pk_add_f32 v[132:133], v[132:133], 1.0 op_sel_hi:[1,0]
	v_pk_add_f32 v[134:135], v[134:135], 1.0 op_sel_hi:[1,0]
	v_rcp_f32_e32 v128, v128
	v_rcp_f32_e32 v129, v129
	v_rcp_f32_e32 v130, v130
	v_rcp_f32_e32 v131, v131
	v_rcp_f32_e32 v132, v132
	v_rcp_f32_e32 v133, v133
	v_rcp_f32_e32 v134, v134
	v_rcp_f32_e32 v135, v135
	v_pk_mul_f32 v[108:109], v[108:109], v[128:129]
	v_pk_mul_f32 v[110:111], v[110:111], v[130:131]
	v_pk_mul_f32 v[104:105], v[104:105], v[132:133]
	v_pk_mul_f32 v[106:107], v[106:107], v[134:135]
	v_pk_mul_f32 v[108:109], v[108:109], v[76:77]
	v_pk_mul_f32 v[110:111], v[110:111], v[78:79]
	v_pk_mul_f32 v[104:105], v[104:105], v[72:73]
	v_pk_mul_f32 v[106:107], v[106:107], v[74:75]
	v_cvt_pk_bf16_f32 v136, v108, v109
	v_cvt_pk_bf16_f32 v137, v110, v111
	v_cvt_pk_bf16_f32 v138, v104, v105
	v_cvt_pk_bf16_f32 v139, v106, v107
	global_store_dwordx4 v218, v[136:139], s[14:15]
	s_waitcnt vmcnt(7)
	v_fmamk_f32 v183, v183, 0x3a800000, v193
	v_rsq_f32_e32 v183, v183
	v_add_u32_e32 v219, 0x42000, v217
	v_pk_mul_f32 v[100:101], v[100:101], v[182:183] op_sel:[0,1] op_sel_hi:[1,1]
	v_pk_mul_f32 v[102:103], v[102:103], v[182:183] op_sel:[0,1] op_sel_hi:[1,1]
	v_pk_mul_f32 v[96:97], v[96:97], v[182:183] op_sel:[0,1] op_sel_hi:[1,1]
	v_pk_mul_f32 v[98:99], v[98:99], v[182:183] op_sel:[0,1] op_sel_hi:[1,1]
	v_pk_mul_f32 v[144:145], v[100:101], v[226:227]
	v_pk_mul_f32 v[146:147], v[102:103], v[226:227]
	v_pk_mul_f32 v[148:149], v[96:97], v[226:227]
	v_pk_mul_f32 v[150:151], v[98:99], v[226:227]
	v_pk_mul_f32 v[68:69], v[68:69], v[182:183] op_sel:[0,1] op_sel_hi:[1,1]
	v_pk_mul_f32 v[70:71], v[70:71], v[182:183] op_sel:[0,1] op_sel_hi:[1,1]
	v_pk_mul_f32 v[64:65], v[64:65], v[182:183] op_sel:[0,1] op_sel_hi:[1,1]
	v_pk_mul_f32 v[66:67], v[66:67], v[182:183] op_sel:[0,1] op_sel_hi:[1,1]
	v_exp_f32_e32 v144, v144
	v_exp_f32_e32 v145, v145
	v_exp_f32_e32 v146, v146
	v_exp_f32_e32 v147, v147
	v_exp_f32_e32 v148, v148
	v_exp_f32_e32 v149, v149
	v_exp_f32_e32 v150, v150
	v_exp_f32_e32 v151, v151
	v_pk_add_f32 v[144:145], v[144:145], 1.0 op_sel_hi:[1,0]
	v_pk_add_f32 v[146:147], v[146:147], 1.0 op_sel_hi:[1,0]
	v_pk_add_f32 v[148:149], v[148:149], 1.0 op_sel_hi:[1,0]
	v_pk_add_f32 v[150:151], v[150:151], 1.0 op_sel_hi:[1,0]
	v_rcp_f32_e32 v144, v144
	v_rcp_f32_e32 v145, v145
	v_rcp_f32_e32 v146, v146
	v_rcp_f32_e32 v147, v147
	v_rcp_f32_e32 v148, v148
	v_rcp_f32_e32 v149, v149
	v_rcp_f32_e32 v150, v150
	v_rcp_f32_e32 v151, v151
	v_pk_mul_f32 v[100:101], v[100:101], v[144:145]
	v_pk_mul_f32 v[102:103], v[102:103], v[146:147]
	v_pk_mul_f32 v[96:97], v[96:97], v[148:149]
	v_pk_mul_f32 v[98:99], v[98:99], v[150:151]
	v_pk_mul_f32 v[100:101], v[100:101], v[68:69]
	v_pk_mul_f32 v[102:103], v[102:103], v[70:71]
	v_pk_mul_f32 v[96:97], v[96:97], v[64:65]
	v_pk_mul_f32 v[98:99], v[98:99], v[66:67]
	v_cvt_pk_bf16_f32 v152, v100, v101
	v_cvt_pk_bf16_f32 v153, v102, v103
	v_cvt_pk_bf16_f32 v154, v96, v97
	v_cvt_pk_bf16_f32 v155, v98, v99
	global_store_dwordx4 v219, v[152:155], s[14:15]
	s_waitcnt vmcnt(7)
	v_fmamk_f32 v184, v184, 0x3a800000, v193
	v_rsq_f32_e32 v184, v184
	v_add_u32_e32 v218, 0xb0000, v217
	v_pk_mul_f32 v[60:61], v[60:61], v[184:185] op_sel_hi:[1,0]
	v_pk_mul_f32 v[62:63], v[62:63], v[184:185] op_sel_hi:[1,0]
	v_pk_mul_f32 v[56:57], v[56:57], v[184:185] op_sel_hi:[1,0]
	v_pk_mul_f32 v[58:59], v[58:59], v[184:185] op_sel_hi:[1,0]
	v_pk_mul_f32 v[128:129], v[60:61], v[226:227]
	v_pk_mul_f32 v[130:131], v[62:63], v[226:227]
	v_pk_mul_f32 v[132:133], v[56:57], v[226:227]
	v_pk_mul_f32 v[134:135], v[58:59], v[226:227]
	v_pk_mul_f32 v[28:29], v[28:29], v[184:185] op_sel_hi:[1,0]
	v_pk_mul_f32 v[30:31], v[30:31], v[184:185] op_sel_hi:[1,0]
	v_pk_mul_f32 v[24:25], v[24:25], v[184:185] op_sel_hi:[1,0]
	v_pk_mul_f32 v[26:27], v[26:27], v[184:185] op_sel_hi:[1,0]
	v_exp_f32_e32 v128, v128
	v_exp_f32_e32 v129, v129
	v_exp_f32_e32 v130, v130
	v_exp_f32_e32 v131, v131
	v_exp_f32_e32 v132, v132
	v_exp_f32_e32 v133, v133
	v_exp_f32_e32 v134, v134
	v_exp_f32_e32 v135, v135
	v_pk_add_f32 v[128:129], v[128:129], 1.0 op_sel_hi:[1,0]
	v_pk_add_f32 v[130:131], v[130:131], 1.0 op_sel_hi:[1,0]
	v_pk_add_f32 v[132:133], v[132:133], 1.0 op_sel_hi:[1,0]
	v_pk_add_f32 v[134:135], v[134:135], 1.0 op_sel_hi:[1,0]
	v_rcp_f32_e32 v128, v128
	v_rcp_f32_e32 v129, v129
	v_rcp_f32_e32 v130, v130
	v_rcp_f32_e32 v131, v131
	v_rcp_f32_e32 v132, v132
	v_rcp_f32_e32 v133, v133
	v_rcp_f32_e32 v134, v134
	v_rcp_f32_e32 v135, v135
	v_pk_mul_f32 v[60:61], v[60:61], v[128:129]
	v_pk_mul_f32 v[62:63], v[62:63], v[130:131]
	v_pk_mul_f32 v[56:57], v[56:57], v[132:133]
	v_pk_mul_f32 v[58:59], v[58:59], v[134:135]
	v_pk_mul_f32 v[60:61], v[60:61], v[28:29]
	v_pk_mul_f32 v[62:63], v[62:63], v[30:31]
	v_pk_mul_f32 v[56:57], v[56:57], v[24:25]
	v_pk_mul_f32 v[58:59], v[58:59], v[26:27]
	v_cvt_pk_bf16_f32 v136, v60, v61
	v_cvt_pk_bf16_f32 v137, v62, v63
	v_cvt_pk_bf16_f32 v138, v56, v57
	v_cvt_pk_bf16_f32 v139, v58, v59
	global_store_dwordx4 v218, v[136:139], s[14:15]
	s_waitcnt vmcnt(7)
; __device__ __forceinline__ u32x4 pack8(f32x4 a, f32x4 b) { u32x4 w; w.x = pk2(a[0], a[1]); w.y = pk2(a[2], a[3]); w.z = pk2(b[0], b[1]); w.w = pk2(b[2], b[3]); return w; }
; __device__ __forceinline__ f32x4 sigm4(f32x4 v) { return (f32x4){sigm(v[0]), sigm(v[1]), sigm(v[2]), sigm(v[3])}; }
; #define FOR_ROWS _Pragma("unroll") for (int ai = 0; ai < 2; ++ai) _Pragma("unroll") for (int m = 0; m < 4; ++m)
; __device__ __forceinline__ void epilogue(const int kind, CParams& p, const f32x4 (&acc)[2][2][4][2], const Unit& u, const int wr, const int wc, const int fr_in, const int fq_in) {
;     ...
;     case E_FFN1: {
;         float rsv[2][4];
;         FOR_ROWS { ROWDEF rsv[ai][m] = p.ss2[row]; }
;         FOR_ROWS { ROWDEF
;             const float rs = rsqrtf(rsv[ai][m] * (1.f / 1024.f) + 1e-6f);
;             const f32x4 g0 = acc[ai][0][m][0] * rs, g1 = acc[ai][0][m][1] * rs, u0 = acc[ai][1][m][0] * rs, u1 = acc[ai][1][m][1] * rs;
;             *(u32x4*)(p.hid + row * DFF + u.pn * 128 + cw) = pack8(g0 * sigm4(g0) * u0, g1 * sigm4(g1) * u1);
;         }
;     } break;
	v_fmamk_f32 v185, v185, 0x3a800000, v193
	v_rsq_f32_e32 v185, v185
	v_add_u32_e32 v219, 0xc6000, v217
	v_pk_mul_f32 v[52:53], v[52:53], v[184:185] op_sel:[0,1] op_sel_hi:[1,1]
	v_pk_mul_f32 v[54:55], v[54:55], v[184:185] op_sel:[0,1] op_sel_hi:[1,1]
	v_pk_mul_f32 v[48:49], v[48:49], v[184:185] op_sel:[0,1] op_sel_hi:[1,1]
	v_pk_mul_f32 v[50:51], v[50:51], v[184:185] op_sel:[0,1] op_sel_hi:[1,1]
	v_pk_mul_f32 v[144:145], v[52:53], v[226:227]
	v_pk_mul_f32 v[146:147], v[54:55], v[226:227]
	v_pk_mul_f32 v[148:149], v[48:49], v[226:227]
	v_pk_mul_f32 v[150:151], v[50:51], v[226:227]
	v_pk_mul_f32 v[20:21], v[20:21], v[184:185] op_sel:[0,1] op_sel_hi:[1,1]
	v_pk_mul_f32 v[22:23], v[22:23], v[184:185] op_sel:[0,1] op_sel_hi:[1,1]
	v_pk_mul_f32 v[16:17], v[16:17], v[184:185] op_sel:[0,1] op_sel_hi:[1,1]
	v_pk_mul_f32 v[18:19], v[18:19], v[184:185] op_sel:[0,1] op_sel_hi:[1,1]
	v_exp_f32_e32 v144, v144
	v_exp_f32_e32 v145, v145
	v_exp_f32_e32 v146, v146
	v_exp_f32_e32 v147, v147
	v_exp_f32_e32 v148, v148
	v_exp_f32_e32 v149, v149
	v_exp_f32_e32 v150, v150
	v_exp_f32_e32 v151, v151
	v_pk_add_f32 v[144:145], v[144:145], 1.0 op_sel_hi:[1,0]
	v_pk_add_f32 v[146:147], v[146:147], 1.0 op_sel_hi:[1,0]
	v_pk_add_f32 v[148:149], v[148:149], 1.0 op_sel_hi:[1,0]
	v_pk_add_f32 v[150:151], v[150:151], 1.0 op_sel_hi:[1,0]
	v_rcp_f32_e32 v144, v144
	v_rcp_f32_e32 v145, v145
	v_rcp_f32_e32 v146, v146
	v_rcp_f32_e32 v147, v147
	v_rcp_f32_e32 v148, v148
	v_rcp_f32_e32 v149, v149
	v_rcp_f32_e32 v150, v150
	v_rcp_f32_e32 v151, v151
	v_pk_mul_f32 v[52:53], v[52:53], v[144:145]
	v_pk_mul_f32 v[54:55], v[54:55], v[146:147]
	v_pk_mul_f32 v[48:49], v[48:49], v[148:149]
	v_pk_mul_f32 v[50:51], v[50:51], v[150:151]
	v_pk_mul_f32 v[52:53], v[52:53], v[20:21]
	v_pk_mul_f32 v[54:55], v[54:55], v[22:23]
	v_pk_mul_f32 v[48:49], v[48:49], v[16:17]
	v_pk_mul_f32 v[50:51], v[50:51], v[18:19]
	v_cvt_pk_bf16_f32 v152, v52, v53
	v_cvt_pk_bf16_f32 v153, v54, v55
	v_cvt_pk_bf16_f32 v154, v48, v49
	v_cvt_pk_bf16_f32 v155, v50, v51
	global_store_dwordx4 v219, v[152:155], s[14:15]
	s_waitcnt vmcnt(7)
	v_fmamk_f32 v186, v186, 0x3a800000, v193
	v_rsq_f32_e32 v186, v186
	v_add_u32_e32 v218, 0xdc000, v217
	v_pk_mul_f32 v[44:45], v[44:45], v[186:187] op_sel_hi:[1,0]
	v_pk_mul_f32 v[46:47], v[46:47], v[186:187] op_sel_hi:[1,0]
	v_pk_mul_f32 v[40:41], v[40:41], v[186:187] op_sel_hi:[1,0]
	v_pk_mul_f32 v[42:43], v[42:43], v[186:187] op_sel_hi:[1,0]
	v_pk_mul_f32 v[128:129], v[44:45], v[226:227]
	v_pk_mul_f32 v[130:131], v[46:47], v[226:227]
	v_pk_mul_f32 v[132:133], v[40:41], v[226:227]
	v_pk_mul_f32 v[134:135], v[42:43], v[226:227]
	v_pk_mul_f32 v[12:13], v[12:13], v[186:187] op_sel_hi:[1,0]
	v_pk_mul_f32 v[14:15], v[14:15], v[186:187] op_sel_hi:[1,0]
	v_pk_mul_f32 v[8:9], v[8:9], v[186:187] op_sel_hi:[1,0]
	v_pk_mul_f32 v[10:11], v[10:11], v[186:187] op_sel_hi:[1,0]
	v_exp_f32_e32 v128, v128
	v_exp_f32_e32 v129, v129
	v_exp_f32_e32 v130, v130
	v_exp_f32_e32 v131, v131
	v_exp_f32_e32 v132, v132
	v_exp_f32_e32 v133, v133
	v_exp_f32_e32 v134, v134
	v_exp_f32_e32 v135, v135
	v_pk_add_f32 v[128:129], v[128:129], 1.0 op_sel_hi:[1,0]
	v_pk_add_f32 v[130:131], v[130:131], 1.0 op_sel_hi:[1,0]
	v_pk_add_f32 v[132:133], v[132:133], 1.0 op_sel_hi:[1,0]
	v_pk_add_f32 v[134:135], v[134:135], 1.0 op_sel_hi:[1,0]
	v_rcp_f32_e32 v128, v128
	v_rcp_f32_e32 v129, v129
	v_rcp_f32_e32 v130, v130
	v_rcp_f32_e32 v131, v131
	v_rcp_f32_e32 v132, v132
	v_rcp_f32_e32 v133, v133
	v_rcp_f32_e32 v134, v134
	v_rcp_f32_e32 v135, v135
	v_pk_mul_f32 v[44:45], v[44:45], v[128:129]
	v_pk_mul_f32 v[46:47], v[46:47], v[130:131]
	v_pk_mul_f32 v[40:41], v[40:41], v[132:133]
	v_pk_mul_f32 v[42:43], v[42:43], v[134:135]
	v_pk_mul_f32 v[44:45], v[44:45], v[12:13]
	v_pk_mul_f32 v[46:47], v[46:47], v[14:15]
	v_pk_mul_f32 v[40:41], v[40:41], v[8:9]
	v_pk_mul_f32 v[42:43], v[42:43], v[10:11]
	v_cvt_pk_bf16_f32 v136, v44, v45
	v_cvt_pk_bf16_f32 v137, v46, v47
	v_cvt_pk_bf16_f32 v138, v40, v41
	v_cvt_pk_bf16_f32 v139, v42, v43
	global_store_dwordx4 v218, v[136:139], s[14:15]
	s_waitcnt vmcnt(7)
	v_fmamk_f32 v187, v187, 0x3a800000, v193
	v_rsq_f32_e32 v187, v187
	v_add_u32_e32 v219, 0xf2000, v217
	v_pk_mul_f32 v[36:37], v[36:37], v[186:187] op_sel:[0,1] op_sel_hi:[1,1]
	v_pk_mul_f32 v[38:39], v[38:39], v[186:187] op_sel:[0,1] op_sel_hi:[1,1]
	v_pk_mul_f32 v[32:33], v[32:33], v[186:187] op_sel:[0,1] op_sel_hi:[1,1]
	v_pk_mul_f32 v[34:35], v[34:35], v[186:187] op_sel:[0,1] op_sel_hi:[1,1]
	v_pk_mul_f32 v[144:145], v[36:37], v[226:227]
	v_pk_mul_f32 v[146:147], v[38:39], v[226:227]
	v_pk_mul_f32 v[148:149], v[32:33], v[226:227]
	v_pk_mul_f32 v[150:151], v[34:35], v[226:227]
	v_pk_mul_f32 v[4:5], v[4:5], v[186:187] op_sel:[0,1] op_sel_hi:[1,1]
	v_pk_mul_f32 v[6:7], v[6:7], v[186:187] op_sel:[0,1] op_sel_hi:[1,1]
	v_pk_mul_f32 v[0:1], v[0:1], v[186:187] op_sel:[0,1] op_sel_hi:[1,1]
	v_pk_mul_f32 v[2:3], v[2:3], v[186:187] op_sel:[0,1] op_sel_hi:[1,1]
	v_exp_f32_e32 v144, v144
	v_exp_f32_e32 v145, v145
	v_exp_f32_e32 v146, v146
	v_exp_f32_e32 v147, v147
	v_exp_f32_e32 v148, v148
	v_exp_f32_e32 v149, v149
	v_exp_f32_e32 v150, v150
	v_exp_f32_e32 v151, v151
	v_pk_add_f32 v[144:145], v[144:145], 1.0 op_sel_hi:[1,0]
	v_pk_add_f32 v[146:147], v[146:147], 1.0 op_sel_hi:[1,0]
	v_pk_add_f32 v[148:149], v[148:149], 1.0 op_sel_hi:[1,0]
	v_pk_add_f32 v[150:151], v[150:151], 1.0 op_sel_hi:[1,0]
	v_rcp_f32_e32 v144, v144
	v_rcp_f32_e32 v145, v145
	v_rcp_f32_e32 v146, v146
	v_rcp_f32_e32 v147, v147
	v_rcp_f32_e32 v148, v148
	v_rcp_f32_e32 v149, v149
	v_rcp_f32_e32 v150, v150
	v_rcp_f32_e32 v151, v151
	v_pk_mul_f32 v[36:37], v[36:37], v[144:145]
	v_pk_mul_f32 v[38:39], v[38:39], v[146:147]
	v_pk_mul_f32 v[32:33], v[32:33], v[148:149]
	v_pk_mul_f32 v[34:35], v[34:35], v[150:151]
	v_pk_mul_f32 v[36:37], v[36:37], v[4:5]
	v_pk_mul_f32 v[38:39], v[38:39], v[6:7]
	v_pk_mul_f32 v[32:33], v[32:33], v[0:1]
	v_pk_mul_f32 v[34:35], v[34:35], v[2:3]
	v_cvt_pk_bf16_f32 v152, v36, v37
	v_cvt_pk_bf16_f32 v153, v38, v39
	v_cvt_pk_bf16_f32 v154, v32, v33
	v_cvt_pk_bf16_f32 v155, v34, v35
	global_store_dwordx4 v219, v[152:155], s[14:15]
	s_nop 1
	s_branch .LBB0_911
